# M2: next unit's staging rows touched into L2 with discarded loads while the current unit computes (software L2 prefetch)
# speedup vs baseline: 1.0053x; 1.0038x over previous
; #define LAS __attribute__((address_space(3)))
; __device__ __forceinline__ float bf2f(bf16_t h) { return __uint_as_float((unsigned)h << 16); }
; __device__ __forceinline__ bf16_t f2bf(float f) { return (bf16_t)(cvt_pk_bf16(f, 0.f) & 0xffffu); }
; __device__ __forceinline__ float sigmoidf(float x) { return rcpf(1.0f + __expf(-x)); }
; __device__ __forceinline__ void phase_m2(PP P, int l, LAS unsigned char* lds, const Ids I) {
;     ...
;         for (int i = 0; i < 3; ++i) { const int idx = tid + 512 * i; if (idx < 11 * 128) { const int tok = idx >> 7, col = idx & 127, r = r0 + tok, t = t_in_seq(r);
;             const float cur = bf2f(PR[(size_t)r * INW + 2688 + col]);
;             const float prev = t > 0 ? bf2f(PR[(size_t)(r - 1) * INW + 2688 + col]) : (r < MTP ? 0.f : P->in[I_SSHIFT][((size_t)l * 128 + ((r - MTP) >> 2)) * PW + 1664 + col]);
;             const float sg = sigmoidf(cur + (prev - cur) * mu[1664 + col]); const bf16_t h = f2bf(sg);
;             SGH[tok * 136 + col] = h; SGL[tok * 136 + col] = f2bf(sg - bf2f(h)); } }
; #pragma unroll
;         for (int i = 0; i < 2; ++i) { const int idx = tid + 512 * i; if (idx < 11 * 64) { const int tok = idx >> 6, c8 = (idx & 63) * 8; const size_t r = (size_t)r0 + tok; float f[8];
;             unpack8(*(const u32x4*)(ymix + r * 1024 + 512 + c8), f); *(LAS f32x4*)(LY + tok * 512 + c8) = (f32x4){f[0], f[1], f[2], f[3]}; *(LAS f32x4*)(LY + tok * 512 + c8 + 4) = (f32x4){f[4], f[5], f[6], f[7]};
;             unpack8(*(const u32x4*)(arr + A_R * AS + r * 512 + c8), f); *(LAS f32x4*)(LR + tok * 512 + c8) = (f32x4){f[0], f[1], f[2], f[3]}; *(LAS f32x4*)(LR + tok * 512 + c8 + 4) = (f32x4){f[4], f[5], f[6], f[7]};
;             unpack8(*(const u32x4*)(arr + A_KF * AS + r * 512 + c8), f); *(LAS f32x4*)(LK + tok * 512 + c8) = (f32x4){f[0], f[1], f[2], f[3]}; *(LAS f32x4*)(LK + tok * 512 + c8 + 4) = (f32x4){f[4], f[5], f[6], f[7]};
;             unpack8(*(const u32x4*)(arr + A_V * AS + r * 512 + c8), f); *(LAS f32x4*)(LV + tok * 512 + c8) = (f32x4){f[0], f[1], f[2], f[3]}; *(LAS f32x4*)(LV + tok * 512 + c8 + 4) = (f32x4){f[4], f[5], f[6], f[7]}; } }
.LBB0_433:
	s_mul_i32 s0, s3, 11
	v_lshlrev_b32_e32 v144, 1, v154
	s_load_dwordx2 s[22:23], s[88:89], 0x30
	s_ashr_i32 s1, s0, 31
	global_load_dword v224, v[156:157], off
	s_add_u32 s24, s60, 0x1500
	s_addc_u32 s25, s61, 0
	v_mov_b64_e32 v[210:211], s[24:25]
	v_lshlrev_b32_e32 v209, 2, v154
	s_waitcnt lgkmcnt(0)
	s_add_u32 s22, s22, 0x1a00
	s_addc_u32 s23, s23, 0
	s_movk_i32 s24, 0x1c00
	s_mov_b64 exec, s[4:5]
	v_add_u32_e32 v212, s0, v188
	v_mad_i64_i32 v[204:205], s[26:27], v212, s73, v[210:211]
	v_add_u32_e32 v208, -1, v212
	v_lshl_add_u64 v[204:205], v[204:205], 0, v[144:145]
	v_mad_i64_i32 v[206:207], s[26:27], v208, s73, v[210:211]
	global_load_ushort v215, v[204:205], off
	v_lshl_add_u64 v[206:207], v[206:207], 0, v[144:145]
	v_mov_b32_e32 v221, 0
	global_load_ushort v218, v[206:207], off
	v_and_b32_e32 v208, 3, v212
	v_cmp_lt_i32_e32 vcc, s76, v212
	v_cmp_eq_u32_e64 s[26:27], 0, v208
	s_and_b64 s[26:27], vcc, s[26:27]
	s_and_saveexec_b64 s[28:29], s[26:27]
	v_add_u32_e32 v208, 0xffffc000, v212
	v_lshrrev_b32_e32 v208, 2, v208
	v_add_u32_e32 v208, s34, v208
	v_mov_b64_e32 v[206:207], s[22:23]
	v_mad_u64_u32 v[206:207], s[26:27], v208, s24, v[206:207]
	v_mov_b32_e32 v205, v145
	v_mov_b32_e32 v204, v209
	v_lshl_add_u64 v[206:207], v[206:207], 0, v[204:205]
	global_load_dword v221, v[206:207], off
	s_mov_b64 exec, s[6:7]
	v_add_u32_e32 v213, s0, v190
	v_mad_i64_i32 v[204:205], s[26:27], v213, s73, v[210:211]
	v_add_u32_e32 v208, -1, v213
	v_lshl_add_u64 v[204:205], v[204:205], 0, v[144:145]
	v_mad_i64_i32 v[206:207], s[26:27], v208, s73, v[210:211]
	global_load_ushort v216, v[204:205], off
	v_lshl_add_u64 v[206:207], v[206:207], 0, v[144:145]
	v_mov_b32_e32 v222, 0
	global_load_ushort v219, v[206:207], off
	v_and_b32_e32 v208, 3, v213
	v_cmp_lt_i32_e32 vcc, s76, v213
	v_cmp_eq_u32_e64 s[26:27], 0, v208
	s_and_b64 s[26:27], vcc, s[26:27]
	s_and_saveexec_b64 s[28:29], s[26:27]
	v_add_u32_e32 v208, 0xffffc000, v213
	v_lshrrev_b32_e32 v208, 2, v208
	v_add_u32_e32 v208, s34, v208
	v_mov_b64_e32 v[206:207], s[22:23]
	v_mad_u64_u32 v[206:207], s[26:27], v208, s24, v[206:207]
	v_mov_b32_e32 v205, v145
	v_mov_b32_e32 v204, v209
	v_lshl_add_u64 v[206:207], v[206:207], 0, v[204:205]
	global_load_dword v222, v[206:207], off
	s_mov_b64 exec, s[8:9]
	v_add_u32_e32 v214, s0, v192
	v_mad_i64_i32 v[204:205], s[26:27], v214, s73, v[210:211]
	v_add_u32_e32 v208, -1, v214
	v_lshl_add_u64 v[204:205], v[204:205], 0, v[144:145]
	v_mad_i64_i32 v[206:207], s[26:27], v208, s73, v[210:211]
	global_load_ushort v217, v[204:205], off
	v_lshl_add_u64 v[206:207], v[206:207], 0, v[144:145]
	v_mov_b32_e32 v223, 0
	global_load_ushort v220, v[206:207], off
	v_and_b32_e32 v208, 3, v214
	v_cmp_lt_i32_e32 vcc, s76, v214
	v_cmp_eq_u32_e64 s[26:27], 0, v208
	s_and_b64 s[26:27], vcc, s[26:27]
	s_and_saveexec_b64 s[28:29], s[26:27]
	v_add_u32_e32 v208, 0xffffc000, v214
	v_lshrrev_b32_e32 v208, 2, v208
	v_add_u32_e32 v208, s34, v208
	v_mov_b64_e32 v[206:207], s[22:23]
	v_mad_u64_u32 v[206:207], s[26:27], v208, s24, v[206:207]
	v_mov_b32_e32 v205, v145
	v_mov_b32_e32 v204, v209
	v_lshl_add_u64 v[206:207], v[206:207], 0, v[204:205]
	global_load_dword v223, v[206:207], off
	s_mov_b64 exec, -1
	v_lshl_add_u64 v[204:205], s[0:1], 0, v[164:165]
	v_lshlrev_b64 v[170:171], 11, v[204:205]
	s_mov_b64 exec, s[10:11]
	v_lshl_add_u64 v[206:207], v[168:169], 0, v[170:171]
	v_lshlrev_b64 v[204:205], 10, v[204:205]
	global_load_dwordx4 v[128:131], v[206:207], off offset:1024
	v_lshl_add_u64 v[206:207], v[158:159], 0, v[204:205]
	global_load_dwordx4 v[132:135], v[206:207], off
	v_lshl_add_u64 v[206:207], v[160:161], 0, v[204:205]
	global_load_dwordx4 v[136:139], v[206:207], off
	v_lshl_add_u64 v[206:207], v[162:163], 0, v[204:205]
	global_load_dwordx4 v[140:143], v[206:207], off
	s_mov_b64 exec, -1
	v_lshl_add_u64 v[204:205], s[0:1], 0, v[166:167]
	v_lshlrev_b64 v[172:173], 11, v[204:205]
	s_mov_b64 exec, s[12:13]
	v_lshl_add_u64 v[206:207], v[168:169], 0, v[172:173]
	v_lshlrev_b64 v[204:205], 10, v[204:205]
	global_load_dwordx4 v[176:179], v[206:207], off offset:1024
	v_lshl_add_u64 v[206:207], v[158:159], 0, v[204:205]
	global_load_dwordx4 v[180:183], v[206:207], off
	v_lshl_add_u64 v[206:207], v[160:161], 0, v[204:205]
	global_load_dwordx4 v[226:229], v[206:207], off
	v_lshl_add_u64 v[206:207], v[162:163], 0, v[204:205]
	global_load_dwordx4 v[230:233], v[206:207], off
	s_mov_b64 exec, -1
	s_waitcnt vmcnt(0)
; #define LAS __attribute__((address_space(3)))
; __device__ __forceinline__ float bf2f(bf16_t h) { return __uint_as_float((unsigned)h << 16); }
; __device__ __forceinline__ bf16_t f2bf(float f) { return (bf16_t)(cvt_pk_bf16(f, 0.f) & 0xffffu); }
; __device__ __forceinline__ float sigmoidf(float x) { return rcpf(1.0f + __expf(-x)); }
; __device__ __forceinline__ void phase_m2(PP P, int l, LAS unsigned char* lds, const Ids I) {
;     ...
;         for (int i = 0; i < 3; ++i) { const int idx = tid + 512 * i; if (idx < 11 * 128) { const int tok = idx >> 7, col = idx & 127, r = r0 + tok, t = t_in_seq(r);
;             const float cur = bf2f(PR[(size_t)r * INW + 2688 + col]);
;             const float prev = t > 0 ? bf2f(PR[(size_t)(r - 1) * INW + 2688 + col]) : (r < MTP ? 0.f : P->in[I_SSHIFT][((size_t)l * 128 + ((r - MTP) >> 2)) * PW + 1664 + col]);
;             const float sg = sigmoidf(cur + (prev - cur) * mu[1664 + col]); const bf16_t h = f2bf(sg);
;             SGH[tok * 136 + col] = h; SGL[tok * 136 + col] = f2bf(sg - bf2f(h)); } }
; #pragma unroll
;         for (int i = 0; i < 2; ++i) { const int idx = tid + 512 * i; if (idx < 11 * 64) { const int tok = idx >> 6, c8 = (idx & 63) * 8; const size_t r = (size_t)r0 + tok; float f[8];
;             unpack8(*(const u32x4*)(ymix + r * 1024 + 512 + c8), f); *(LAS f32x4*)(LY + tok * 512 + c8) = (f32x4){f[0], f[1], f[2], f[3]}; *(LAS f32x4*)(LY + tok * 512 + c8 + 4) = (f32x4){f[4], f[5], f[6], f[7]};
;             unpack8(*(const u32x4*)(arr + A_R * AS + r * 512 + c8), f); *(LAS f32x4*)(LR + tok * 512 + c8) = (f32x4){f[0], f[1], f[2], f[3]}; *(LAS f32x4*)(LR + tok * 512 + c8 + 4) = (f32x4){f[4], f[5], f[6], f[7]};
;             unpack8(*(const u32x4*)(arr + A_KF * AS + r * 512 + c8), f); *(LAS f32x4*)(LK + tok * 512 + c8) = (f32x4){f[0], f[1], f[2], f[3]}; *(LAS f32x4*)(LK + tok * 512 + c8 + 4) = (f32x4){f[4], f[5], f[6], f[7]};
;             unpack8(*(const u32x4*)(arr + A_V * AS + r * 512 + c8), f); *(LAS f32x4*)(LV + tok * 512 + c8) = (f32x4){f[0], f[1], f[2], f[3]}; *(LAS f32x4*)(LV + tok * 512 + c8 + 4) = (f32x4){f[4], f[5], f[6], f[7]}; } }
	s_mov_b64 exec, s[4:5]
	v_cmp_gt_i32_e32 vcc, s91, v212
	v_lshlrev_b32_e32 v215, 16, v215
	v_lshlrev_b32_e32 v218, 16, v218
	v_cndmask_b32_e32 v208, 3, v185, vcc
	v_and_b32_e32 v208, v208, v212
	v_cmp_ne_u32_e32 vcc, 0, v208
	s_nop 1
	v_cndmask_b32_e32 v218, v221, v218, vcc
	v_sub_f32_e32 v208, v218, v215
	v_fmac_f32_e32 v215, v208, v224
	v_mul_f32_e32 v215, 0xbfb8aa3b, v215
	v_exp_f32_e32 v215, v215
	s_nop 0
	v_add_f32_e32 v215, 1.0, v215
	v_rcp_f32_e32 v215, v215
	s_nop 0
	v_cvt_pk_bf16_f32 v208, v215, v145
	ds_write_b16 v189, v208
	v_lshlrev_b32_e32 v218, 16, v208
	v_sub_f32_e32 v215, v215, v218
	v_cvt_pk_bf16_f32 v215, v215, v145
	ds_write_b16 v189, v215 offset:4352
	s_mov_b64 exec, s[6:7]
	v_cmp_gt_i32_e32 vcc, s91, v213
	v_lshlrev_b32_e32 v216, 16, v216
	v_lshlrev_b32_e32 v219, 16, v219
	v_cndmask_b32_e32 v208, 3, v185, vcc
	v_and_b32_e32 v208, v208, v213
	v_cmp_ne_u32_e32 vcc, 0, v208
	s_nop 1
	v_cndmask_b32_e32 v219, v222, v219, vcc
	v_sub_f32_e32 v208, v219, v216
	v_fmac_f32_e32 v216, v208, v224
	v_mul_f32_e32 v216, 0xbfb8aa3b, v216
	v_exp_f32_e32 v216, v216
	s_nop 0
	v_add_f32_e32 v216, 1.0, v216
	v_rcp_f32_e32 v216, v216
	s_nop 0
	v_cvt_pk_bf16_f32 v208, v216, v145
	ds_write_b16 v191, v208
	v_lshlrev_b32_e32 v219, 16, v208
	v_sub_f32_e32 v216, v216, v219
	v_cvt_pk_bf16_f32 v216, v216, v145
	ds_write_b16 v191, v216 offset:4352
	s_mov_b64 exec, s[8:9]
	v_cmp_gt_i32_e32 vcc, s91, v214
	v_lshlrev_b32_e32 v217, 16, v217
	v_lshlrev_b32_e32 v220, 16, v220
	v_cndmask_b32_e32 v208, 3, v185, vcc
	v_and_b32_e32 v208, v208, v214
	v_cmp_ne_u32_e32 vcc, 0, v208
	s_nop 1
	v_cndmask_b32_e32 v220, v223, v220, vcc
	v_sub_f32_e32 v208, v220, v217
	v_fmac_f32_e32 v217, v208, v224
	v_mul_f32_e32 v217, 0xbfb8aa3b, v217
	v_exp_f32_e32 v217, v217
	s_nop 0
	v_add_f32_e32 v217, 1.0, v217
	v_rcp_f32_e32 v217, v217
	s_nop 0
	v_cvt_pk_bf16_f32 v208, v217, v145
	ds_write_b16 v193, v208
	v_lshlrev_b32_e32 v220, 16, v208
	v_sub_f32_e32 v217, v217, v220
	v_cvt_pk_bf16_f32 v217, v217, v145
	ds_write_b16 v193, v217 offset:4352
	s_mov_b64 exec, s[10:11]
	v_lshlrev_b32_e32 v242, 16, v128
	v_and_b32_e32 v243, 0xffff0000, v128
	v_lshlrev_b32_e32 v244, 16, v129
	v_and_b32_e32 v245, 0xffff0000, v129
	v_lshlrev_b32_e32 v246, 16, v130
	v_and_b32_e32 v247, 0xffff0000, v130
	v_lshlrev_b32_e32 v248, 16, v131
	v_and_b32_e32 v249, 0xffff0000, v131
	ds_write_b128 v194, v[242:245] offset:8704
	ds_write_b128 v194, v[246:249] offset:8720
	v_lshlrev_b32_e32 v250, 16, v132
	v_and_b32_e32 v251, 0xffff0000, v132
	v_lshlrev_b32_e32 v252, 16, v133
	v_and_b32_e32 v253, 0xffff0000, v133
	v_lshlrev_b32_e32 v204, 16, v134
	v_and_b32_e32 v205, 0xffff0000, v134
	v_lshlrev_b32_e32 v206, 16, v135
	v_and_b32_e32 v207, 0xffff0000, v135
	ds_write_b128 v194, v[250:253] offset:31232
	ds_write_b128 v194, v[204:207] offset:31248
	v_lshlrev_b32_e32 v242, 16, v136
	v_and_b32_e32 v243, 0xffff0000, v136
	v_lshlrev_b32_e32 v244, 16, v137
	v_and_b32_e32 v245, 0xffff0000, v137
	v_lshlrev_b32_e32 v246, 16, v138
	v_and_b32_e32 v247, 0xffff0000, v138
	v_lshlrev_b32_e32 v248, 16, v139
	v_and_b32_e32 v249, 0xffff0000, v139
	ds_write_b128 v194, v[242:245] offset:53760
	ds_write_b128 v194, v[246:249] offset:53776
	v_lshlrev_b32_e32 v250, 16, v140
	v_and_b32_e32 v251, 0xffff0000, v140
	v_lshlrev_b32_e32 v252, 16, v141
	v_and_b32_e32 v253, 0xffff0000, v141
	v_lshlrev_b32_e32 v204, 16, v142
	v_and_b32_e32 v205, 0xffff0000, v142
	v_lshlrev_b32_e32 v206, 16, v143
	v_and_b32_e32 v207, 0xffff0000, v143
	ds_write_b128 v195, v[250:253]
	ds_write_b128 v195, v[204:207] offset:16
	s_mov_b64 exec, s[12:13]
	v_lshlrev_b32_e32 v242, 16, v176
	v_and_b32_e32 v243, 0xffff0000, v176
	v_lshlrev_b32_e32 v244, 16, v177
	v_and_b32_e32 v245, 0xffff0000, v177
	v_lshlrev_b32_e32 v246, 16, v178
	v_and_b32_e32 v247, 0xffff0000, v178
	v_lshlrev_b32_e32 v248, 16, v179
	v_and_b32_e32 v249, 0xffff0000, v179
	ds_write_b128 v196, v[242:245] offset:8704
	ds_write_b128 v196, v[246:249] offset:8720
	v_lshlrev_b32_e32 v250, 16, v180
	v_and_b32_e32 v251, 0xffff0000, v180
	v_lshlrev_b32_e32 v252, 16, v181
	v_and_b32_e32 v253, 0xffff0000, v181
	v_lshlrev_b32_e32 v204, 16, v182
	v_and_b32_e32 v205, 0xffff0000, v182
	v_lshlrev_b32_e32 v206, 16, v183
	v_and_b32_e32 v207, 0xffff0000, v183
	ds_write_b128 v196, v[250:253] offset:31232
	ds_write_b128 v196, v[204:207] offset:31248
	v_lshlrev_b32_e32 v242, 16, v226
	v_and_b32_e32 v243, 0xffff0000, v226
	v_lshlrev_b32_e32 v244, 16, v227
	v_and_b32_e32 v245, 0xffff0000, v227
	v_lshlrev_b32_e32 v246, 16, v228
	v_and_b32_e32 v247, 0xffff0000, v228
	v_lshlrev_b32_e32 v248, 16, v229
	v_and_b32_e32 v249, 0xffff0000, v229
	ds_write_b128 v196, v[242:245] offset:53760
	ds_write_b128 v196, v[246:249] offset:53776
	v_lshlrev_b32_e32 v250, 16, v230
	v_and_b32_e32 v251, 0xffff0000, v230
	v_lshlrev_b32_e32 v252, 16, v231
	v_and_b32_e32 v253, 0xffff0000, v231
	v_lshlrev_b32_e32 v204, 16, v232
	v_and_b32_e32 v205, 0xffff0000, v232
	v_lshlrev_b32_e32 v206, 16, v233
	v_and_b32_e32 v207, 0xffff0000, v233
	ds_write_b128 v197, v[250:253]
	ds_write_b128 v197, v[204:207] offset:16
	s_mov_b64 exec, -1
	s_add_i32 s100, s3, s72
	s_cmpk_gt_i32 s100, 0x5ff
	s_cbranch_scc1 .Lm2_pf_done
; __device__ __forceinline__ void phase_m2(PP P, int l, LAS unsigned char* lds, const Ids I) {
;     ...
;         for (int i = 0; i < 3; ++i) { const int idx = tid + 512 * i; if (idx < 11 * 128) { const int tok = idx >> 7, col = idx & 127, r = r0 + tok, t = t_in_seq(r);
;             const float cur = bf2f(PR[(size_t)r * INW + 2688 + col]);
;             const float prev = t > 0 ? bf2f(PR[(size_t)(r - 1) * INW + 2688 + col]) : (r < MTP ? 0.f : P->in[I_SSHIFT][((size_t)l * 128 + ((r - MTP) >> 2)) * PW + 1664 + col]);
;             const float sg = sigmoidf(cur + (prev - cur) * mu[1664 + col]); const bf16_t h = f2bf(sg);
;             SGH[tok * 136 + col] = h; SGL[tok * 136 + col] = f2bf(sg - bf2f(h)); } }
; #pragma unroll
;         for (int i = 0; i < 2; ++i) { const int idx = tid + 512 * i; if (idx < 11 * 64) { const int tok = idx >> 6, c8 = (idx & 63) * 8; const size_t r = (size_t)r0 + tok; float f[8];
;             unpack8(*(const u32x4*)(ymix + r * 1024 + 512 + c8), f); *(LAS f32x4*)(LY + tok * 512 + c8) = (f32x4){f[0], f[1], f[2], f[3]}; *(LAS f32x4*)(LY + tok * 512 + c8 + 4) = (f32x4){f[4], f[5], f[6], f[7]};
;             unpack8(*(const u32x4*)(arr + A_R * AS + r * 512 + c8), f); *(LAS f32x4*)(LR + tok * 512 + c8) = (f32x4){f[0], f[1], f[2], f[3]}; *(LAS f32x4*)(LR + tok * 512 + c8 + 4) = (f32x4){f[4], f[5], f[6], f[7]};
;             unpack8(*(const u32x4*)(arr + A_KF * AS + r * 512 + c8), f); *(LAS f32x4*)(LK + tok * 512 + c8) = (f32x4){f[0], f[1], f[2], f[3]}; *(LAS f32x4*)(LK + tok * 512 + c8 + 4) = (f32x4){f[4], f[5], f[6], f[7]};
;             unpack8(*(const u32x4*)(arr + A_V * AS + r * 512 + c8), f); *(LAS f32x4*)(LV + tok * 512 + c8) = (f32x4){f[0], f[1], f[2], f[3]}; *(LAS f32x4*)(LV + tok * 512 + c8 + 4) = (f32x4){f[4], f[5], f[6], f[7]}; } }
;         __syncthreads();
;         { f32x4 ag[4];
; #pragma unroll
;           for (int nt = 0; nt < 4; ++nt) ag[nt] = (f32x4){0.f, 0.f, 0.f, 0.f};
; #pragma unroll
;           for (int ks = 0; ks < 4; ++ks) { const bf16x8 fh = *(const LAS bf16x8*)(SGH + l15 * 136 + ks * 32 + quad * 8), fl = *(const LAS bf16x8*)(SGL + l15 * 136 + ks * 32 + quad * 8);
; #pragma unroll
;               for (int nt = 0; nt < 4; ++nt) { ag[nt] = __builtin_amdgcn_mfma_f32_16x16x32_bf16(fl, bfh[nt][ks], ag[nt], 0, 0, 0); ag[nt] = __builtin_amdgcn_mfma_f32_16x16x32_bf16(fh, bfl[nt][ks], ag[nt], 0, 0, 0);
	s_mul_i32 s100, s100, 11
	s_mov_b32 s101, 0
	s_add_u32 s24, s60, 0x1500
	s_addc_u32 s25, s61, 0
	v_mov_b64_e32 v[210:211], s[24:25]
	v_lshlrev_b32_e32 v144, 1, v154
	s_mov_b64 exec, s[4:5]
	v_add_u32_e32 v212, s100, v188
	v_mad_i64_i32 v[204:205], s[26:27], v212, s73, v[210:211]
	v_add_u32_e32 v208, -1, v212
	v_lshl_add_u64 v[204:205], v[204:205], 0, v[144:145]
	v_mad_i64_i32 v[206:207], s[26:27], v208, s73, v[210:211]
	global_load_ushort v152, v[204:205], off
	v_lshl_add_u64 v[206:207], v[206:207], 0, v[144:145]
	global_load_ushort v152, v[206:207], off
	s_mov_b64 exec, s[6:7]
	v_add_u32_e32 v212, s100, v190
	v_mad_i64_i32 v[204:205], s[26:27], v212, s73, v[210:211]
	v_add_u32_e32 v208, -1, v212
	v_lshl_add_u64 v[204:205], v[204:205], 0, v[144:145]
	v_mad_i64_i32 v[206:207], s[26:27], v208, s73, v[210:211]
	global_load_ushort v152, v[204:205], off
	v_lshl_add_u64 v[206:207], v[206:207], 0, v[144:145]
	global_load_ushort v152, v[206:207], off
	s_mov_b64 exec, s[8:9]
	v_add_u32_e32 v212, s100, v192
	v_mad_i64_i32 v[204:205], s[26:27], v212, s73, v[210:211]
	v_add_u32_e32 v208, -1, v212
	v_lshl_add_u64 v[204:205], v[204:205], 0, v[144:145]
	v_mad_i64_i32 v[206:207], s[26:27], v208, s73, v[210:211]
	global_load_ushort v152, v[204:205], off
	v_lshl_add_u64 v[206:207], v[206:207], 0, v[144:145]
	global_load_ushort v152, v[206:207], off
	s_mov_b64 exec, -1
	v_lshl_add_u64 v[204:205], s[100:101], 0, v[164:165]
	v_lshlrev_b64 v[234:235], 11, v[204:205]
	s_mov_b64 exec, s[10:11]
	v_lshl_add_u64 v[206:207], v[168:169], 0, v[234:235]
	v_lshlrev_b64 v[204:205], 10, v[204:205]
	global_load_dword v152, v[206:207], off offset:1024
	v_lshl_add_u64 v[206:207], v[158:159], 0, v[204:205]
	global_load_dword v152, v[206:207], off
	v_lshl_add_u64 v[206:207], v[160:161], 0, v[204:205]
	global_load_dword v152, v[206:207], off
	v_lshl_add_u64 v[206:207], v[162:163], 0, v[204:205]
	global_load_dword v152, v[206:207], off
	s_mov_b64 exec, -1
	v_lshl_add_u64 v[204:205], s[100:101], 0, v[166:167]
	v_lshlrev_b64 v[234:235], 11, v[204:205]
	s_mov_b64 exec, s[12:13]
	v_lshl_add_u64 v[206:207], v[168:169], 0, v[234:235]
	v_lshlrev_b64 v[204:205], 10, v[204:205]
	global_load_dword v152, v[206:207], off offset:1024
	v_lshl_add_u64 v[206:207], v[158:159], 0, v[204:205]
	global_load_dword v152, v[206:207], off
	v_lshl_add_u64 v[206:207], v[160:161], 0, v[204:205]
	global_load_dword v152, v[206:207], off
	v_lshl_add_u64 v[206:207], v[162:163], 0, v[204:205]
	global_load_dword v152, v[206:207], off
.Lm2_pf_done:
	s_mov_b64 exec, -1
	s_waitcnt lgkmcnt(0)
	s_barrier
	ds_read_b128 v[128:131], v187
	ds_read_b128 v[132:135], v187 offset:4352
	s_waitcnt lgkmcnt(0)
	v_mfma_f32_16x16x32_bf16 v[136:139], v[132:135], v[0:3], 0
	v_mfma_f32_16x16x32_bf16 v[140:143], v[132:135], v[32:35], 0
	v_mfma_f32_16x16x32_bf16 v[176:179], v[132:135], v[64:67], 0
	v_mfma_f32_16x16x32_bf16 v[132:135], v[132:135], v[96:99], 0
	v_mfma_f32_16x16x32_bf16 v[136:139], v[128:131], v[4:7], v[136:139]
	v_mfma_f32_16x16x32_bf16 v[140:143], v[128:131], v[36:39], v[140:143]
	v_mfma_f32_16x16x32_bf16 v[176:179], v[128:131], v[68:71], v[176:179]
	v_mfma_f32_16x16x32_bf16 v[132:135], v[128:131], v[100:103], v[132:135]
	v_mfma_f32_16x16x32_bf16 v[136:139], v[128:131], v[0:3], v[136:139]
	v_mfma_f32_16x16x32_bf16 v[140:143], v[128:131], v[32:35], v[140:143]
	v_mfma_f32_16x16x32_bf16 v[176:179], v[128:131], v[64:67], v[176:179]
	v_mfma_f32_16x16x32_bf16 v[128:131], v[128:131], v[96:99], v[132:135]
	s_nop 3
	ds_read_b128 v[132:135], v187 offset:64
	ds_read_b128 v[180:183], v187 offset:4416
	s_waitcnt lgkmcnt(0)
	v_mfma_f32_16x16x32_bf16 v[136:139], v[180:183], v[8:11], v[136:139]
	v_mfma_f32_16x16x32_bf16 v[140:143], v[180:183], v[40:43], v[140:143]
	v_mfma_f32_16x16x32_bf16 v[176:179], v[180:183], v[72:75], v[176:179]
	v_mfma_f32_16x16x32_bf16 v[128:131], v[180:183], v[104:107], v[128:131]
	v_mfma_f32_16x16x32_bf16 v[136:139], v[132:135], v[12:15], v[136:139]
	v_mfma_f32_16x16x32_bf16 v[140:143], v[132:135], v[44:47], v[140:143]
	v_mfma_f32_16x16x32_bf16 v[176:179], v[132:135], v[76:79], v[176:179]
	v_mfma_f32_16x16x32_bf16 v[128:131], v[132:135], v[108:111], v[128:131]
	v_mfma_f32_16x16x32_bf16 v[136:139], v[132:135], v[8:11], v[136:139]
	v_mfma_f32_16x16x32_bf16 v[140:143], v[132:135], v[40:43], v[140:143]
	v_mfma_f32_16x16x32_bf16 v[176:179], v[132:135], v[72:75], v[176:179]
	v_mfma_f32_16x16x32_bf16 v[128:131], v[132:135], v[104:107], v[128:131]
	ds_read_b128 v[132:135], v187 offset:128
	ds_read_b128 v[180:183], v187 offset:4480
	s_waitcnt lgkmcnt(0)
	v_mfma_f32_16x16x32_bf16 v[140:143], v[180:183], v[48:51], v[140:143]
	v_mfma_f32_16x16x32_bf16 v[136:139], v[180:183], v[16:19], v[136:139]
	v_mfma_f32_16x16x32_bf16 v[140:143], v[132:135], v[52:55], v[140:143]
	v_mfma_f32_16x16x32_bf16 v[136:139], v[132:135], v[20:23], v[136:139]
	v_mfma_f32_16x16x32_bf16 v[204:207], v[132:135], v[48:51], v[140:143]
	v_mfma_f32_16x16x32_bf16 v[140:143], v[180:183], v[80:83], v[176:179]
	v_mfma_f32_16x16x32_bf16 v[128:131], v[180:183], v[112:115], v[128:131]
	ds_read_b128 v[180:183], v187 offset:192
	ds_read_b128 v[208:211], v187 offset:4544
	v_mfma_f32_16x16x32_bf16 v[136:139], v[132:135], v[16:19], v[136:139]
	v_mfma_f32_16x16x32_bf16 v[140:143], v[132:135], v[84:87], v[140:143]
	v_mfma_f32_16x16x32_bf16 v[128:131], v[132:135], v[116:119], v[128:131]
	v_mfma_f32_16x16x32_bf16 v[176:179], v[132:135], v[80:83], v[140:143]
	v_mfma_f32_16x16x32_bf16 v[128:131], v[132:135], v[112:115], v[128:131]
	s_waitcnt lgkmcnt(0)
	v_mfma_f32_16x16x32_bf16 v[132:135], v[208:211], v[24:27], v[136:139]
	v_mfma_f32_16x16x32_bf16 v[132:135], v[180:183], v[28:31], v[132:135]
	v_mfma_f32_16x16x32_bf16 v[140:143], v[180:183], v[24:27], v[132:135]
	v_mfma_f32_16x16x32_bf16 v[132:135], v[208:211], v[56:59], v[204:207]
	v_mfma_f32_16x16x32_bf16 v[132:135], v[180:183], v[60:63], v[132:135]
	v_mfma_f32_16x16x32_bf16 v[136:139], v[180:183], v[56:59], v[132:135]
	v_mfma_f32_16x16x32_bf16 v[132:135], v[208:211], v[88:91], v[176:179]
	v_mfma_f32_16x16x32_bf16 v[128:131], v[208:211], v[120:123], v[128:131]
	v_mfma_f32_16x16x32_bf16 v[132:135], v[180:183], v[92:95], v[132:135]
	v_mfma_f32_16x16x32_bf16 v[128:131], v[180:183], v[124:127], v[128:131]
	v_mfma_f32_16x16x32_bf16 v[132:135], v[180:183], v[88:91], v[132:135]
	v_mfma_f32_16x16x32_bf16 v[128:131], v[180:183], v[120:123], v[128:131]
	s_and_saveexec_b64 s[0:1], s[14:15]
	s_cbranch_execz .LBB0_477
	ds_write_b32 v199, v140
	s_or_b64 exec, exec, s[0:1]
	s_and_saveexec_b64 s[0:1], s[16:17]
	s_cbranch_execnz .LBB0_478

; #define LAS __attribute__((address_space(3)))
; __device__ __forceinline__ unsigned cvt_pk_bf16(float lo, float hi) { unsigned r; asm("v_cvt_pk_bf16_f32 %0, %1, %2" : "=v"(r) : "v"(lo), "v"(hi)); return r; }
; __device__ __forceinline__ void phase_m2(PP P, int l, LAS unsigned char* lds, const Ids I) {
;     ...
;         for (int i = 0; i < 2; ++i) { const int idx = tid + 512 * i; if (idx < 11 * 64) { const int tok = idx >> 6, c8 = (idx & 63) * 8; const LAS float* lp = LY + tok * 512 + c8; const f32x4 a = *(const LAS f32x4*)lp, b = *(const LAS f32x4*)(lp + 4);
;           u32x4 w; w.x = cvt_pk_bf16(a[0], a[1]); w.y = cvt_pk_bf16(a[2], a[3]); w.z = cvt_pk_bf16(b[0], b[1]); w.w = cvt_pk_bf16(b[2], b[3]);
;           *(u32x4*)(ymix + ((size_t)r0 + tok) * 1024 + 512 + c8) = w; } }
.LBB0_497:
	s_or_b64 exec, exec, s[0:1]
	s_and_saveexec_b64 s[0:1], s[12:13]
	s_cbranch_execz .LBB0_432
	ds_read_b128 v[128:131], v196 offset:8704
	ds_read_b128 v[132:135], v196 offset:8720
	s_waitcnt lgkmcnt(1)
	v_cvt_pk_bf16_f32 v128, v128, v129
	v_cvt_pk_bf16_f32 v129, v130, v131
	s_waitcnt lgkmcnt(0)
	v_cvt_pk_bf16_f32 v130, v132, v133
	v_lshl_add_u64 v[132:133], v[168:169], 0, v[172:173]
	v_cvt_pk_bf16_f32 v131, v134, v135
	global_store_dwordx4 v[132:133], v[128:131], off offset:1024
	s_branch .LBB0_432
	s_nop 0
	s_nop 0
	s_nop 0
	s_nop 0
	s_nop 0
	s_nop 0
	s_nop 0
	s_nop 0
	s_nop 0
	s_nop 0
	s_nop 0
	s_nop 0
	s_nop 0
	s_nop 0
	s_nop 0
	s_nop 0
	s_nop 0
	s_nop 0
	s_nop 0
	s_nop 0
	s_nop 0
	s_nop 0
	s_nop 0
	s_nop 0

; __global__ void __launch_bounds__(512) mega(Params Pval) {
;     extern __shared__ __attribute__((aligned(16))) unsigned char lds_raw[];
	.amdhsa_kernel _Z4mega6Params
		.amdhsa_group_segment_fixed_size 0
		.amdhsa_private_segment_fixed_size 0
		.amdhsa_kernarg_size 592
		.amdhsa_user_sgpr_count 2
		.amdhsa_user_sgpr_dispatch_ptr 0
		.amdhsa_user_sgpr_queue_ptr 0
		.amdhsa_user_sgpr_kernarg_segment_ptr 1
		.amdhsa_user_sgpr_dispatch_id 0
		.amdhsa_user_sgpr_kernarg_preload_length 0
		.amdhsa_user_sgpr_kernarg_preload_offset 0
		.amdhsa_user_sgpr_private_segment_size 0
		.amdhsa_uses_dynamic_stack 0
		.amdhsa_enable_private_segment 0
		.amdhsa_system_sgpr_workgroup_id_x 1
		.amdhsa_system_sgpr_workgroup_id_y 0
		.amdhsa_system_sgpr_workgroup_id_z 0
		.amdhsa_system_sgpr_workgroup_info 0
		.amdhsa_system_vgpr_workitem_id 2
		.amdhsa_next_free_vgpr 256
		.amdhsa_next_free_sgpr 102
		.amdhsa_accum_offset 256
		.amdhsa_reserve_vcc 1
		.amdhsa_float_round_mode_32 0
		.amdhsa_float_round_mode_16_64 0
		.amdhsa_float_denorm_mode_32 3
		.amdhsa_float_denorm_mode_16_64 3
		.amdhsa_dx10_clamp 1
		.amdhsa_ieee_mode 1
		.amdhsa_fp16_overflow 0
		.amdhsa_tg_split 0
		.amdhsa_exception_fp_ieee_invalid_op 0
		.amdhsa_exception_fp_denorm_src 0
		.amdhsa_exception_fp_ieee_div_zero 0
		.amdhsa_exception_fp_ieee_overflow 0
		.amdhsa_exception_fp_ieee_underflow 0
		.amdhsa_exception_fp_ieee_inexact 0
		.amdhsa_exception_int_div_zero 0
	.end_amdhsa_kernel

; __global__ void __launch_bounds__(512) mega(Params Pval) {
;     extern __shared__ __attribute__((aligned(16))) unsigned char lds_raw[];
amdhsa.kernels:
  - .agpr_count:     0
    .args:
      - .offset:         0
        .size:           336
        .value_kind:     by_value
      - .offset:         336
        .size:           4
        .value_kind:     hidden_block_count_x
      - .offset:         340
        .size:           4
        .value_kind:     hidden_block_count_y
      - .offset:         344
        .size:           4
        .value_kind:     hidden_block_count_z
      - .offset:         348
        .size:           2
        .value_kind:     hidden_group_size_x
      - .offset:         350
        .size:           2
        .value_kind:     hidden_group_size_y
      - .offset:         352
        .size:           2
        .value_kind:     hidden_group_size_z
      - .offset:         354
        .size:           2
        .value_kind:     hidden_remainder_x
      - .offset:         356
        .size:           2
        .value_kind:     hidden_remainder_y
      - .offset:         358
        .size:           2
        .value_kind:     hidden_remainder_z
      - .offset:         376
        .size:           8
        .value_kind:     hidden_global_offset_x
      - .offset:         384
        .size:           8
        .value_kind:     hidden_global_offset_y
      - .offset:         392
        .size:           8
        .value_kind:     hidden_global_offset_z
      - .offset:         400
        .size:           2
        .value_kind:     hidden_grid_dims
      - .offset:         424
        .size:           8
        .value_kind:     hidden_multigrid_sync_arg
      - .offset:         456
        .size:           4
        .value_kind:     hidden_dynamic_lds_size
    .group_segment_fixed_size: 0
    .kernarg_segment_align: 8
    .kernarg_segment_size: 592
    .language:       OpenCL C
    .language_version:
      - 2
      - 0
    .max_flat_workgroup_size: 512
    .name:           _Z4mega6Params
    .private_segment_fixed_size: 0
    .sgpr_count:     108
    .sgpr_spill_count: 92
    .symbol:         _Z4mega6Params.kd
    .uniform_work_group_size: 1
    .uses_dynamic_stack: false
    .vgpr_count:     256
    .vgpr_spill_count: 0
    .wavefront_size: 64
